# phase A GEMM k-loop re-interleaved by hand: same instructions, staging ds_write/global_load and fragment ds_reads spread one or two per MFMA gap, own address temporaries per staging unit, all waitcnts
# speedup vs baseline: 1.1256x; 1.0316x over previous
.LBB0_343:
	s_bitcmp1_b32 s2, 0
	s_cselect_b32 s3, 0x12000, 0
	v_add_u32_e32 v28, s3, v27
	v_add_u32_e32 v40, v28, v25
	ds_read_b128 v[50:53], v40 offset:4608
	v_add_u32_e32 v49, v28, v26
	ds_read_b128 v[128:131], v49 offset:36864
	ds_read_b128 v[168:171], v49 offset:41472
	ds_read_b128 v[136:139], v49 offset:46080
	ds_read_b128 v[176:179], v49 offset:50688
	ds_read_b128 v[144:147], v40
	ds_read_b128 v[152:155], v40 offset:9216
	ds_read_b128 v[160:163], v40 offset:13824
	s_add_i32 s3, s2, 1
	s_bitcmp1_b32 s3, 0
	s_cselect_b32 s6, 0x12000, 0
	s_cmp_lt_u32 s2, 14
	s_cselect_b32 s90, s9, 0
	v_add_u32_e32 v184, s6, v22
	v_add_u32_e32 v185, v184, v23
	s_waitcnt lgkmcnt(6)
	v_mfma_f32_32x32x16_f16 a[192:207], v[50:53], v[128:131], a[192:207]
	ds_read_b128 v[124:127], v40 offset:4640
	ds_read_b128 v[132:135], v49 offset:36896
	ds_read_b128 v[140:143], v49 offset:46112
	s_waitcnt lgkmcnt(8)
	v_mfma_f32_32x32x16_f16 a[208:223], v[50:53], v[168:171], a[208:223]
	ds_read_b128 v[148:151], v40 offset:32
	ds_read_b128 v[156:159], v40 offset:9248
	ds_read_b128 v[164:167], v40 offset:13856
	s_waitcnt lgkmcnt(10)
	v_mfma_f32_32x32x16_f16 a[64:79], v[50:53], v[136:139], a[64:79]
	ds_read_b128 v[172:175], v49 offset:41504
	ds_read_b128 v[180:183], v49 offset:50720
	s_lshl_b64 s[6:7], s[90:91], 1
	s_waitcnt lgkmcnt(11)
	v_mfma_f32_32x32x16_f16 a[80:95], v[50:53], v[176:179], a[80:95]
	v_lshl_add_u64 v[28:29], v[18:19], 0, s[6:7]
	v_lshl_add_u64 v[78:79], v[20:21], 0, s[6:7]
	ds_read_b128 v[50:53], v40 offset:64
	s_waitcnt lgkmcnt(11)
	v_mfma_f32_32x32x16_f16 a[224:239], v[144:147], v[128:131], a[224:239]
	s_waitcnt vmcnt(15)
	ds_write_b128 v185, v[58:61]
	v_lshl_add_u64 v[186:187], v[28:29], 0, v[0:1]
	v_mfma_f32_32x32x16_f16 a[240:255], v[144:147], v[168:171], a[240:255]
	global_load_dwordx4 v[58:61], v[186:187], off
	s_waitcnt vmcnt(15)
	ds_write_b128 v185, v[54:57] offset:4608
	v_mfma_f32_32x32x16_f16 a[96:111], v[144:147], v[136:139], a[96:111]
	v_lshl_add_u64 v[188:189], v[28:29], 0, v[2:3]
	global_load_dwordx4 v[54:57], v[188:189], off
	v_mfma_f32_32x32x16_f16 a[112:127], v[144:147], v[176:179], a[112:127]
	ds_read_b128 v[144:147], v40 offset:13888
	s_waitcnt lgkmcnt(13)
	v_mfma_f32_32x32x16_f16 a[160:175], v[152:155], v[128:131], a[160:175]
	v_mfma_f32_32x32x16_f16 a[176:191], v[152:155], v[168:171], a[176:191]
	s_waitcnt vmcnt(9)
	ds_write_b128 v185, v[92:95] offset:36864
	v_lshl_add_u64 v[190:191], v[78:79], 0, v[0:1]
	v_mfma_f32_32x32x16_f16 a[32:47], v[152:155], v[136:139], a[32:47]
	global_load_dwordx4 v[92:95], v[190:191], off
	v_mfma_f32_32x32x16_f16 a[48:63], v[152:155], v[176:179], a[48:63]
	ds_read_b128 v[152:155], v49 offset:36928
	s_waitcnt lgkmcnt(14)
	v_mfma_f32_32x32x16_f16 a[128:143], v[160:163], v[128:131], a[128:143]
	ds_read_b128 v[128:131], v40 offset:4672
	s_waitcnt vmcnt(9)
	ds_write_b128 v185, v[96:99] offset:41472
	v_mfma_f32_32x32x16_f16 a[144:159], v[160:163], v[168:171], a[144:159]
	ds_read_b128 v[168:171], v49 offset:46144
	v_lshl_add_u64 v[192:193], v[78:79], 0, v[2:3]
	global_load_dwordx4 v[96:99], v[192:193], off
	v_mfma_f32_32x32x16_f16 a[16:31], v[160:163], v[136:139], a[16:31]
	ds_read_b128 v[136:139], v40 offset:9280
	v_mfma_f32_32x32x16_f16 a[0:15], v[160:163], v[176:179], a[0:15]
	ds_read_b128 v[160:163], v49 offset:41536
	ds_read_b128 v[176:179], v49 offset:50752
	s_waitcnt lgkmcnt(15)
	v_mfma_f32_32x32x16_f16 a[224:239], v[148:151], v[132:135], a[224:239]
	ds_write_b128 v185, v[66:69] offset:9216
	v_lshl_add_u64 v[194:195], v[28:29], 0, v[4:5]
	s_waitcnt lgkmcnt(14)
	v_mfma_f32_32x32x16_f16 a[240:255], v[148:151], v[172:175], a[240:255]
	global_load_dwordx4 v[66:69], v[194:195], off
	v_mfma_f32_32x32x16_f16 a[96:111], v[148:151], v[140:143], a[96:111]
	s_waitcnt lgkmcnt(13)
	v_mfma_f32_32x32x16_f16 a[112:127], v[148:151], v[180:183], a[112:127]
	ds_read_b128 v[148:151], v40 offset:13920
	v_mfma_f32_32x32x16_f16 a[192:207], v[124:127], v[132:135], a[192:207]
	ds_write_b128 v185, v[62:65] offset:13824
	v_lshl_add_u64 v[196:197], v[28:29], 0, v[6:7]
	v_mfma_f32_32x32x16_f16 a[208:223], v[124:127], v[172:175], a[208:223]
	global_load_dwordx4 v[62:65], v[196:197], off
	v_mfma_f32_32x32x16_f16 a[64:79], v[124:127], v[140:143], a[64:79]
	v_mfma_f32_32x32x16_f16 a[80:95], v[124:127], v[180:183], a[80:95]
	ds_read_b128 v[124:127], v40 offset:96
	s_waitcnt vmcnt(11)
	ds_write_b128 v185, v[100:103] offset:46080
	v_mfma_f32_32x32x16_f16 a[160:175], v[156:159], v[132:135], a[160:175]
	v_lshl_add_u64 v[198:199], v[78:79], 0, v[4:5]
	global_load_dwordx4 v[100:103], v[198:199], off
	v_mfma_f32_32x32x16_f16 a[176:191], v[156:159], v[172:175], a[176:191]
	v_mfma_f32_32x32x16_f16 a[32:47], v[156:159], v[140:143], a[32:47]
	v_mfma_f32_32x32x16_f16 a[48:63], v[156:159], v[180:183], a[48:63]
	ds_read_b128 v[156:159], v49 offset:36960
	s_waitcnt vmcnt(11)
	ds_write_b128 v185, v[104:107] offset:50688
	v_mfma_f32_32x32x16_f16 a[128:143], v[164:167], v[132:135], a[128:143]
	ds_read_b128 v[132:135], v40 offset:4704
	v_lshl_add_u64 v[200:201], v[78:79], 0, v[6:7]
	global_load_dwordx4 v[104:107], v[200:201], off
	v_mfma_f32_32x32x16_f16 a[144:159], v[164:167], v[172:175], a[144:159]
	ds_read_b128 v[172:175], v49 offset:46176
	v_mfma_f32_32x32x16_f16 a[16:31], v[164:167], v[140:143], a[16:31]
	ds_read_b128 v[140:143], v40 offset:9312
	v_add_u32_e32 v40, v184, v24
	ds_write_b128 v185, v[70:73] offset:18432
	v_mfma_f32_32x32x16_f16 a[0:15], v[164:167], v[180:183], a[0:15]
	ds_read_b128 v[164:167], v49 offset:41568
	ds_read_b128 v[180:183], v49 offset:50784
	v_lshl_add_u64 v[202:203], v[28:29], 0, v[8:9]
	s_waitcnt lgkmcnt(15)
	v_mfma_f32_32x32x16_f16 a[224:239], v[50:53], v[152:155], a[224:239]
	global_load_dwordx4 v[70:73], v[202:203], off
	s_waitcnt lgkmcnt(14)
	v_mfma_f32_32x32x16_f16 a[240:255], v[50:53], v[160:163], a[240:255]
	v_mfma_f32_32x32x16_f16 a[96:111], v[50:53], v[168:171], a[96:111]
	ds_write_b128 v185, v[74:77] offset:23040
	v_lshl_add_u64 v[204:205], v[28:29], 0, v[10:11]
	s_waitcnt lgkmcnt(14)
	v_mfma_f32_32x32x16_f16 a[112:127], v[50:53], v[176:179], a[112:127]
	global_load_dwordx4 v[74:77], v[204:205], off
	v_mfma_f32_32x32x16_f16 a[192:207], v[128:131], v[152:155], a[192:207]
	v_mfma_f32_32x32x16_f16 a[208:223], v[128:131], v[160:163], a[208:223]
	v_mfma_f32_32x32x16_f16 a[64:79], v[128:131], v[168:171], a[64:79]
	s_waitcnt vmcnt(13)
	ds_write_b128 v185, v[108:111] offset:55296
	v_lshl_add_u64 v[206:207], v[78:79], 0, v[8:9]
	v_mfma_f32_32x32x16_f16 a[80:95], v[128:131], v[176:179], a[80:95]
	global_load_dwordx4 v[108:111], v[206:207], off
	v_mfma_f32_32x32x16_f16 a[160:175], v[136:139], v[152:155], a[160:175]
	v_mfma_f32_32x32x16_f16 a[176:191], v[136:139], v[160:163], a[176:191]
	s_waitcnt vmcnt(13)
	ds_write_b128 v185, v[112:115] offset:59904
	v_lshl_add_u64 v[208:209], v[78:79], 0, v[10:11]
	v_mfma_f32_32x32x16_f16 a[32:47], v[136:139], v[168:171], a[32:47]
	global_load_dwordx4 v[112:115], v[208:209], off
	v_mfma_f32_32x32x16_f16 a[48:63], v[136:139], v[176:179], a[48:63]
	v_mfma_f32_32x32x16_f16 a[128:143], v[144:147], v[152:155], a[128:143]
	v_mfma_f32_32x32x16_f16 a[144:159], v[144:147], v[160:163], a[144:159]
	ds_write_b128 v185, v[84:87] offset:27648
	v_lshl_add_u64 v[210:211], v[28:29], 0, v[14:15]
	v_mfma_f32_32x32x16_f16 a[16:31], v[144:147], v[168:171], a[16:31]
	global_load_dwordx4 v[84:87], v[210:211], off
	v_mfma_f32_32x32x16_f16 a[0:15], v[144:147], v[176:179], a[0:15]
	s_waitcnt lgkmcnt(11)
	v_mfma_f32_32x32x16_f16 a[224:239], v[124:127], v[156:159], a[224:239]
	ds_write_b128 v185, v[88:91] offset:32256
	v_lshl_add_u64 v[212:213], v[28:29], 0, v[16:17]
	s_waitcnt lgkmcnt(6)
	v_mfma_f32_32x32x16_f16 a[240:255], v[124:127], v[164:167], a[240:255]
	global_load_dwordx4 v[88:91], v[212:213], off
	v_mfma_f32_32x32x16_f16 a[96:111], v[124:127], v[172:175], a[96:111]
	s_waitcnt lgkmcnt(5)
	v_mfma_f32_32x32x16_f16 a[112:127], v[124:127], v[180:183], a[112:127]
	v_mfma_f32_32x32x16_f16 a[192:207], v[132:135], v[156:159], a[192:207]
	s_waitcnt vmcnt(15)
	ds_write_b128 v185, v[116:119] offset:64512
	v_lshl_add_u64 v[214:215], v[78:79], 0, v[14:15]
	v_mfma_f32_32x32x16_f16 a[208:223], v[132:135], v[164:167], a[208:223]
	global_load_dwordx4 v[116:119], v[214:215], off
	v_mfma_f32_32x32x16_f16 a[64:79], v[132:135], v[172:175], a[64:79]
	v_mfma_f32_32x32x16_f16 a[80:95], v[132:135], v[180:183], a[80:95]
	v_mfma_f32_32x32x16_f16 a[160:175], v[140:143], v[156:159], a[160:175]
	s_waitcnt vmcnt(15)
	ds_write_b128 v40, v[120:123] offset:55296
	v_lshl_add_u64 v[216:217], v[78:79], 0, v[16:17]
	v_mfma_f32_32x32x16_f16 a[176:191], v[140:143], v[164:167], a[176:191]
	global_load_dwordx4 v[120:123], v[216:217], off
	v_mfma_f32_32x32x16_f16 a[32:47], v[140:143], v[172:175], a[32:47]
	v_mfma_f32_32x32x16_f16 a[48:63], v[140:143], v[180:183], a[48:63]
	v_mfma_f32_32x32x16_f16 a[128:143], v[148:151], v[156:159], a[128:143]
	v_mfma_f32_32x32x16_f16 a[144:159], v[148:151], v[164:167], a[144:159]
	v_mfma_f32_32x32x16_f16 a[16:31], v[148:151], v[172:175], a[16:31]
	v_mfma_f32_32x32x16_f16 a[0:15], v[148:151], v[180:183], a[0:15]
	s_waitcnt lgkmcnt(0)
	s_barrier
	s_add_i32 s9, s9, 64
	s_cmp_lg_u32 s3, 16
	s_mov_b32 s2, s3
	s_cbranch_scc1 .LBB0_343
	s_add_i32 s45, s45, 1
	s_cmp_ge_i32 s45, s41
	s_mov_b32 s46, s8
	s_mov_b32 s47, s48
	s_cbranch_scc1 .LBB0_350
	s_mov_b64 s[2:3], -1
	s_and_b64 vcc, exec, s[22:23]
	s_cbranch_vccz .LBB0_347
	v_readlane_b32 s12, v253, 2
	v_readlane_b32 s14, v253, 4
	s_mul_i32 s2, s45, s14
	s_add_i32 s2, s2, s54
	v_readlane_b32 s13, v253, 3
	v_readlane_b32 s15, v253, 5
	s_and_b32 s46, s2, 63
	s_ashr_i32 s47, s2, 6
	s_mov_b64 s[2:3], 0
